# P6 residual epilogue rewritten: 16 x-loads in flight per wave with counted vmcnt instead of 32 serialized load/wait(0)/store round trips
# speedup vs baseline: 1.0823x; 1.0049x over previous
.LBB0_566:
	v_lshl_add_u32 v152, s28, 8, v142
	v_lshl_or_b32 v154, s54, 8, v144
	v_ashrrev_i32_e32 v153, 31, v152
	v_ashrrev_i32_e32 v155, 31, v154
	v_lshlrev_b64 v[140:141], 11, v[152:153]
	v_lshl_add_u64 v[140:141], v[140:141], 0, v[154:155]
	v_lshlrev_b64 v[140:141], 2, v[140:141]
	s_andn2_b64 vcc, exec, s[0:1]
	s_mov_b64 s[0:1], -1
	v_mov_b32_e32 v224, v140
	v_or_b32_e32 v225, 16, v152
	v_lshl_add_u32 v225, v225, 11, v154
	v_lshlrev_b32_e32 v225, 2, v225
	v_or_b32_e32 v226, 32, v152
	v_lshl_add_u32 v226, v226, 11, v154
	v_lshlrev_b32_e32 v226, 2, v226
	v_or_b32_e32 v227, 48, v152
	v_lshl_add_u32 v227, v227, 11, v154
	v_lshlrev_b32_e32 v227, 2, v227
	v_add_u32_e32 v228, s10, v140
	v_add_u32_e32 v229, s12, v140
	v_add_u32_e32 v230, s14, v140
	v_add_u32_e32 v231, s18, v140
	global_load_dwordx4 v[160:163], v224, s[16:17]
	global_load_dwordx4 v[164:167], v224, s[16:17] offset:64
	global_load_dwordx4 v[168:171], v224, s[16:17] offset:512
	global_load_dwordx4 v[172:175], v224, s[16:17] offset:576
	global_load_dwordx4 v[176:179], v225, s[16:17]
	global_load_dwordx4 v[180:183], v225, s[16:17] offset:64
	global_load_dwordx4 v[184:187], v225, s[16:17] offset:512
	global_load_dwordx4 v[188:191], v225, s[16:17] offset:576
	global_load_dwordx4 v[192:195], v226, s[16:17]
	global_load_dwordx4 v[196:199], v226, s[16:17] offset:64
	global_load_dwordx4 v[200:203], v226, s[16:17] offset:512
	global_load_dwordx4 v[204:207], v226, s[16:17] offset:576
	global_load_dwordx4 v[208:211], v227, s[16:17]
	global_load_dwordx4 v[212:215], v227, s[16:17] offset:64
	global_load_dwordx4 v[216:219], v227, s[16:17] offset:512
	global_load_dwordx4 v[220:223], v227, s[16:17] offset:576
	s_waitcnt vmcnt(15)
	v_pk_add_f32 v[124:125], v[124:125], v[160:161]
	v_pk_add_f32 v[126:127], v[126:127], v[162:163]
	global_store_dwordx4 v224, v[124:127], s[50:51]
	global_load_dwordx4 v[160:163], v228, s[16:17]
	s_waitcnt vmcnt(16)
	v_pk_add_f32 v[120:121], v[120:121], v[164:165]
	v_pk_add_f32 v[122:123], v[122:123], v[166:167]
	global_store_dwordx4 v224, v[120:123], s[50:51] offset:64
	global_load_dwordx4 v[164:167], v228, s[16:17] offset:64
	s_waitcnt vmcnt(17)
	v_pk_add_f32 v[116:117], v[116:117], v[168:169]
	v_pk_add_f32 v[118:119], v[118:119], v[170:171]
	global_store_dwordx4 v224, v[116:119], s[50:51] offset:512
	global_load_dwordx4 v[168:171], v228, s[16:17] offset:512
	s_waitcnt vmcnt(18)
	v_pk_add_f32 v[104:105], v[104:105], v[172:173]
	v_pk_add_f32 v[106:107], v[106:107], v[174:175]
	global_store_dwordx4 v224, v[104:107], s[50:51] offset:576
	global_load_dwordx4 v[172:175], v228, s[16:17] offset:576
	s_waitcnt vmcnt(19)
	v_pk_add_f32 v[112:113], v[112:113], v[176:177]
	v_pk_add_f32 v[114:115], v[114:115], v[178:179]
	global_store_dwordx4 v225, v[112:115], s[50:51]
	global_load_dwordx4 v[176:179], v229, s[16:17]
	s_waitcnt vmcnt(20)
	v_pk_add_f32 v[108:109], v[108:109], v[180:181]
	v_pk_add_f32 v[110:111], v[110:111], v[182:183]
	global_store_dwordx4 v225, v[108:111], s[50:51] offset:64
	global_load_dwordx4 v[180:183], v229, s[16:17] offset:64
	s_waitcnt vmcnt(21)
	v_pk_add_f32 v[100:101], v[100:101], v[184:185]
	v_pk_add_f32 v[102:103], v[102:103], v[186:187]
	global_store_dwordx4 v225, v[100:103], s[50:51] offset:512
	global_load_dwordx4 v[184:187], v229, s[16:17] offset:512
	s_waitcnt vmcnt(22)
	v_pk_add_f32 v[88:89], v[88:89], v[188:189]
	v_pk_add_f32 v[90:91], v[90:91], v[190:191]
	global_store_dwordx4 v225, v[88:91], s[50:51] offset:576
	global_load_dwordx4 v[188:191], v229, s[16:17] offset:576
	s_waitcnt vmcnt(23)
	v_pk_add_f32 v[96:97], v[96:97], v[192:193]
	v_pk_add_f32 v[98:99], v[98:99], v[194:195]
	global_store_dwordx4 v226, v[96:99], s[50:51]
	global_load_dwordx4 v[192:195], v230, s[16:17]
	s_waitcnt vmcnt(24)
	v_pk_add_f32 v[92:93], v[92:93], v[196:197]
	v_pk_add_f32 v[94:95], v[94:95], v[198:199]
	global_store_dwordx4 v226, v[92:95], s[50:51] offset:64
	global_load_dwordx4 v[196:199], v230, s[16:17] offset:64
	s_waitcnt vmcnt(25)
	v_pk_add_f32 v[84:85], v[84:85], v[200:201]
	v_pk_add_f32 v[86:87], v[86:87], v[202:203]
	global_store_dwordx4 v226, v[84:87], s[50:51] offset:512
	global_load_dwordx4 v[200:203], v230, s[16:17] offset:512
	s_waitcnt vmcnt(26)
	v_pk_add_f32 v[72:73], v[72:73], v[204:205]
	v_pk_add_f32 v[74:75], v[74:75], v[206:207]
	global_store_dwordx4 v226, v[72:75], s[50:51] offset:576
	global_load_dwordx4 v[204:207], v230, s[16:17] offset:576
	s_waitcnt vmcnt(27)
	v_pk_add_f32 v[80:81], v[80:81], v[208:209]
	v_pk_add_f32 v[82:83], v[82:83], v[210:211]
	global_store_dwordx4 v227, v[80:83], s[50:51]
	global_load_dwordx4 v[208:211], v231, s[16:17]
	s_waitcnt vmcnt(28)
	v_pk_add_f32 v[76:77], v[76:77], v[212:213]
	v_pk_add_f32 v[78:79], v[78:79], v[214:215]
	global_store_dwordx4 v227, v[76:79], s[50:51] offset:64
	global_load_dwordx4 v[212:215], v231, s[16:17] offset:64
	s_waitcnt vmcnt(29)
	v_pk_add_f32 v[68:69], v[68:69], v[216:217]
	v_pk_add_f32 v[70:71], v[70:71], v[218:219]
	global_store_dwordx4 v227, v[68:71], s[50:51] offset:512
	global_load_dwordx4 v[216:219], v231, s[16:17] offset:512
	s_waitcnt vmcnt(30)
	v_pk_add_f32 v[64:65], v[64:65], v[220:221]
	v_pk_add_f32 v[66:67], v[66:67], v[222:223]
	global_store_dwordx4 v227, v[64:67], s[50:51] offset:576
	global_load_dwordx4 v[220:223], v231, s[16:17] offset:576
	s_waitcnt vmcnt(30)
	v_pk_add_f32 v[60:61], v[60:61], v[160:161]
	v_pk_add_f32 v[62:63], v[62:63], v[162:163]
	global_store_dwordx4 v228, v[60:63], s[50:51]
	s_waitcnt vmcnt(29)
	v_pk_add_f32 v[56:57], v[56:57], v[164:165]
	v_pk_add_f32 v[58:59], v[58:59], v[166:167]
	global_store_dwordx4 v228, v[56:59], s[50:51] offset:64
	s_waitcnt vmcnt(28)
	v_pk_add_f32 v[52:53], v[52:53], v[168:169]
	v_pk_add_f32 v[54:55], v[54:55], v[170:171]
	global_store_dwordx4 v228, v[52:55], s[50:51] offset:512
	s_waitcnt vmcnt(27)
	v_pk_add_f32 v[40:41], v[40:41], v[172:173]
	v_pk_add_f32 v[42:43], v[42:43], v[174:175]
	global_store_dwordx4 v228, v[40:43], s[50:51] offset:576
	s_waitcnt vmcnt(26)
	v_pk_add_f32 v[48:49], v[48:49], v[176:177]
	v_pk_add_f32 v[50:51], v[50:51], v[178:179]
	global_store_dwordx4 v229, v[48:51], s[50:51]
	s_waitcnt vmcnt(25)
	v_pk_add_f32 v[44:45], v[44:45], v[180:181]
	v_pk_add_f32 v[46:47], v[46:47], v[182:183]
	global_store_dwordx4 v229, v[44:47], s[50:51] offset:64
	s_waitcnt vmcnt(24)
	v_pk_add_f32 v[36:37], v[36:37], v[184:185]
	v_pk_add_f32 v[38:39], v[38:39], v[186:187]
	global_store_dwordx4 v229, v[36:39], s[50:51] offset:512
	s_waitcnt vmcnt(23)
	v_pk_add_f32 v[24:25], v[24:25], v[188:189]
	v_pk_add_f32 v[26:27], v[26:27], v[190:191]
	global_store_dwordx4 v229, v[24:27], s[50:51] offset:576
	s_waitcnt vmcnt(22)
	v_pk_add_f32 v[32:33], v[32:33], v[192:193]
	v_pk_add_f32 v[34:35], v[34:35], v[194:195]
	global_store_dwordx4 v230, v[32:35], s[50:51]
	s_waitcnt vmcnt(21)
	v_pk_add_f32 v[28:29], v[28:29], v[196:197]
	v_pk_add_f32 v[30:31], v[30:31], v[198:199]
	global_store_dwordx4 v230, v[28:31], s[50:51] offset:64
	s_waitcnt vmcnt(20)
	v_pk_add_f32 v[20:21], v[20:21], v[200:201]
	v_pk_add_f32 v[22:23], v[22:23], v[202:203]
	global_store_dwordx4 v230, v[20:23], s[50:51] offset:512
	s_waitcnt vmcnt(19)
	v_pk_add_f32 v[8:9], v[8:9], v[204:205]
	v_pk_add_f32 v[10:11], v[10:11], v[206:207]
	global_store_dwordx4 v230, v[8:11], s[50:51] offset:576
	s_waitcnt vmcnt(18)
	v_pk_add_f32 v[16:17], v[16:17], v[208:209]
	v_pk_add_f32 v[18:19], v[18:19], v[210:211]
	global_store_dwordx4 v231, v[16:19], s[50:51]
	s_waitcnt vmcnt(17)
	v_pk_add_f32 v[12:13], v[12:13], v[212:213]
	v_pk_add_f32 v[14:15], v[14:15], v[214:215]
	global_store_dwordx4 v231, v[12:15], s[50:51] offset:64
	s_waitcnt vmcnt(16)
	v_pk_add_f32 v[4:5], v[4:5], v[216:217]
	v_pk_add_f32 v[6:7], v[6:7], v[218:219]
	global_store_dwordx4 v231, v[4:7], s[50:51] offset:512
	s_waitcnt vmcnt(15)
	v_pk_add_f32 v[0:1], v[0:1], v[220:221]
	v_pk_add_f32 v[2:3], v[2:3], v[222:223]
	global_store_dwordx4 v231, v[0:3], s[50:51] offset:576
	s_cbranch_vccnz .LBB0_555
	s_andn2_b64 vcc, exec, s[4:5]
	s_cbranch_vccnz .LBB0_554
	s_barrier
	s_branch .LBB0_554
